# GEMM1 tail round split into two 128-row half units (skip ai=1 MFMAs and stores), same scheme as proj/up
# baseline (speedup 1.0000x reference)
.LBB0_287:
	v_mov_b32_e32 v135, v185
	v_lshl_add_u64 v[8:9], s[28:29], 0, v[134:135]
	v_mov_b32_e32 v139, v185
	s_add_i32 s68, s58, 0x18000
	v_lshl_add_u64 v[10:11], s[28:29], 0, v[138:139]
	v_mov_b32_e32 v133, v185
	s_and_b32 s49, s20, 3
	v_lshl_add_u64 v[8:9], v[8:9], 0, s[24:25]
	s_mov_b32 m0, s68
	s_add_i32 s69, s58, 0x1a000
	v_lshl_add_u64 v[12:13], s[0:1], 0, v[132:133]
	v_mov_b32_e32 v137, v185
	s_lshl_b32 s66, s22, 6
	s_lshl_b32 s20, s22, 13
	s_lshl_b32 s23, s49, 12
	s_waitcnt vmcnt(2)
	s_barrier
	global_load_lds_dwordx4 v[8:9], off
	v_lshl_add_u64 v[8:9], v[10:11], 0, s[24:25]
	s_mov_b32 m0, s69
	s_add_i32 s70, s58, 0x8000
	s_add_i32 s71, s58, 0xa000
	v_lshl_add_u64 v[14:15], s[0:1], 0, v[136:137]
	global_load_lds_dwordx4 v[8:9], off
	v_lshl_add_u64 v[8:9], v[12:13], 0, s[24:25]
	s_mov_b32 m0, s70
	s_add_u32 s26, s28, 0x40080
	global_load_lds_dwordx4 v[8:9], off
	v_lshl_add_u64 v[8:9], v[14:15], 0, s[24:25]
	s_mov_b32 m0, s71
	s_addc_u32 s27, s29, 0
	s_add_i32 s52, s58, 0x1c000
	global_load_lds_dwordx4 v[8:9], off
	v_lshl_add_u64 v[8:9], s[26:27], 0, v[134:135]
	s_mov_b32 m0, s52
	s_add_i32 s50, s58, 0x1e000
	global_load_lds_dwordx4 v[8:9], off
	v_lshl_add_u64 v[8:9], s[26:27], 0, v[138:139]
	s_mov_b32 m0, s50
	v_bfe_u32 v7, v0, 4, 2
	global_load_lds_dwordx4 v[8:9], off
	v_and_b32_e32 v140, 15, v0
	v_lshlrev_b32_e32 v142, 4, v7
	v_lshlrev_b32_e32 v0, 2, v0
	v_lshlrev_b32_e32 v8, 3, v7
	v_lshl_or_b32 v7, v140, 6, v142
	v_and_b32_e32 v0, 32, v0
	v_bitop3_b32 v141, v7, s20, v0 bitop3:0xde
	v_bitop3_b32 v143, v7, s23, v0 bitop3:0xde
	v_lshlrev_b32_e32 v0, 14, v1
	s_lshl_b32 s67, s22, 2
	v_and_b32_e32 v0, 0xffff8000, v0
	s_add_i32 s4, s67, 8
	v_lshl_add_u32 v0, v2, 11, v0
	v_and_b32_e32 v1, 1, v1
	v_writelane_b32 v255, s4, 47
	s_add_i32 s4, s67, 9
	v_lshl_or_b32 v0, v1, 6, v0
	v_writelane_b32 v255, s4, 49
	s_add_i32 s4, s67, 10
	v_lshl_add_u32 v148, v3, 1, v0
	v_lshlrev_b32_e32 v0, 14, v4
	v_writelane_b32 v255, s4, 50
	s_add_i32 s4, s67, 11
	v_and_b32_e32 v0, 0xffff8000, v0
	s_waitcnt vmcnt(6)
	v_lshl_or_b32 v144, s49, 5, v8
	v_writelane_b32 v255, s4, 51
	s_nop 1
	v_lshl_add_u32 v0, v5, 11, v0
	v_and_b32_e32 v1, 1, v4
	v_lshlrev_b32_e32 v184, 1, v144
	v_readlane_b32 s12, v253, 24
	v_readlane_b32 s13, v253, 25
	v_lshl_or_b32 v0, v1, 6, v0
	s_or_b32 s48, s49, 0xffffffc0
	v_mov_b32_e32 v145, v185
	s_or_b32 s84, s67, 1
	s_or_b32 s85, s67, 2
	s_or_b32 s92, s67, 3
	v_or_b32_e32 v156, 0x80, v144
	s_orn2_b32 s49, s49, 59
	v_lshl_add_u64 v[146:147], s[12:13], 0, v[184:185]
	v_mov_b32_e32 v149, v185
	v_lshl_add_u32 v150, v6, 1, v0
	v_mov_b32_e32 v151, v185
	s_mov_b32 s65, 0
	s_barrier
	s_nop 1
	s_mov_b32 s100, 0
	s_mov_b32 s101, 0
	s_branch .LBB0_289

.LBB0_288:
	s_cmp_eq_u32 s100, 2
	s_cselect_b32 vcc_lo, 8, 0
	s_sub_i32 s67, s67, vcc_lo
	s_sub_i32 s84, s84, vcc_lo
	s_sub_i32 s85, s85, vcc_lo
	s_sub_i32 s92, s92, vcc_lo
	s_mov_b32 s100, s101
	s_and_b64 vcc, exec, s[22:23]
	s_mov_b32 s33, s54
	s_mov_b32 s38, s40
	s_mov_b32 s53, s55
	s_mov_b64 s[28:29], s[44:45]
	s_mov_b64 s[0:1], s[42:43]
	s_cbranch_vccnz .LBB0_476
.LBB0_289:
	v_readlane_b32 s4, v254, 0
	v_readlane_b32 s5, v254, 1
	s_load_dword s20, s[4:5], 0x0
	s_add_i32 s65, s65, 1
	s_waitcnt lgkmcnt(0)
	s_mul_i32 s20, s65, s20
	s_add_i32 s20, s20, s96
	s_mov_b32 s101, 0
	s_lshr_b32 s26, s51, 8
	s_cmp_lg_u32 s65, s26
	s_cbranch_scc1 .Lg1h_nohalf
	s_and_b32 s27, s51, 0xff
	s_cmp_gt_u32 s27, 0x80
	s_cbranch_scc1 .Lg1h_nohalf
	s_lshl_b32 s27, s27, 1
	s_lshl_b32 s26, s26, 8
	s_lshr_b32 s20, s96, 1
	s_add_i32 s20, s20, s26
	s_cmp_lt_u32 s96, s27
	s_cselect_b32 s20, s20, 0x7fffffff
	s_and_b32 s101, s96, 1
	s_add_i32 s101, s101, 1
.Lg1h_nohalf:
	s_cmp_lt_i32 s20, s51
	s_cselect_b64 s[30:31], -1, 0
	s_cmp_ge_i32 s20, s51
	s_cselect_b64 s[22:23], -1, 0
	s_and_b64 vcc, exec, s[22:23]
	s_cbranch_vccnz .LBB0_298
	s_cmp_ge_i32 s20, s83
	s_mov_b64 s[34:35], -1
	s_cbranch_scc0 .LBB0_296
	s_cmp_ge_i32 s20, s90
	s_cbranch_scc0 .LBB0_293
	s_sub_i32 s26, s20, s90
	s_and_b32 s27, s20, 7
	s_lshr_b32 s26, s26, 3
	s_or_b32 s55, s27, 64
	s_add_i32 s40, s26, 1
	s_mov_b64 s[34:35], 0

.LBB0_298:
	s_lshl_b32 s20, s55, 8
	s_addk_i32 s20, 0x1800
	s_cmp_eq_u32 s54, 0
	s_nop 1
	s_cselect_b32 s26, s55, s20
	v_readlane_b32 s6, v253, 18
	v_readlane_b32 s7, v253, 19
	s_cselect_b32 s20, 19, 11
	s_cselect_b32 s34, s7, s57
	s_cselect_b32 s35, s6, s56
	s_cselect_b32 s36, s56, s6
	s_cselect_b32 s37, s57, s7
	s_ashr_i32 s27, s26, 31
	s_lshl_b64 s[26:27], s[26:27], s20
	s_add_u32 s42, s35, s26
	s_addc_u32 s43, s34, s27
	s_cmp_eq_u32 s101, 2
	s_cselect_b32 s26, 0x40000, 0
	s_add_u32 s42, s42, s26
	s_addc_u32 s43, s43, 0
	s_and_b64 s[26:27], s[30:31], exec
	s_cselect_b32 s20, s43, s1
	s_cselect_b32 s34, s42, s0
	s_ashr_i32 s41, s40, 31
	s_lshl_b64 s[26:27], s[40:41], 19
	s_add_u32 s44, s36, s26
	s_addc_u32 s45, s37, s27
	s_and_b64 s[26:27], s[30:31], exec
	s_cselect_b32 s35, s45, s29
	s_cselect_b32 s36, s44, s28
	s_add_u32 s0, s0, 0x40080
	s_addc_u32 s1, s1, 0
	s_add_u32 s37, s28, 0x100
	v_mov_b32_e32 v0, 0
	s_addc_u32 s26, s29, 0
	s_mov_b32 s27, -2
	v_mov_b32_e32 v1, v0
	v_mov_b64_e32 v[2:3], 0
	v_mov_b64_e32 v[4:5], 0
	v_mov_b64_e32 v[6:7], 0
	v_mov_b64_e32 v[8:9], 0
	v_mov_b64_e32 v[10:11], 0
	v_mov_b64_e32 v[12:13], 0
	v_mov_b64_e32 v[14:15], 0
	v_mov_b64_e32 v[16:17], 0
	v_mov_b64_e32 v[18:19], 0
	v_mov_b64_e32 v[20:21], 0
	v_mov_b64_e32 v[22:23], 0
	v_mov_b64_e32 v[24:25], 0
	v_mov_b64_e32 v[26:27], 0
	v_mov_b64_e32 v[28:29], 0
	v_mov_b64_e32 v[30:31], 0
	v_mov_b64_e32 v[32:33], 0
	v_mov_b64_e32 v[34:35], 0
	v_mov_b64_e32 v[36:37], 0
	v_mov_b64_e32 v[38:39], 0
	v_mov_b64_e32 v[40:41], 0
	v_mov_b64_e32 v[42:43], 0
	v_mov_b64_e32 v[44:45], 0
	v_mov_b64_e32 v[46:47], 0
	v_mov_b64_e32 v[48:49], 0
	v_mov_b64_e32 v[50:51], 0
	v_mov_b64_e32 v[52:53], 0
	v_mov_b64_e32 v[54:55], 0
	v_mov_b64_e32 v[56:57], 0
	v_mov_b64_e32 v[58:59], 0
	v_mov_b64_e32 v[60:61], 0
	v_mov_b64_e32 v[62:63], 0
	v_mov_b64_e32 v[64:65], 0
	v_mov_b64_e32 v[66:67], 0
	v_mov_b64_e32 v[68:69], 0
	v_mov_b64_e32 v[70:71], 0
	v_mov_b64_e32 v[72:73], 0
	v_mov_b64_e32 v[74:75], 0
	v_mov_b64_e32 v[76:77], 0
	v_mov_b64_e32 v[78:79], 0
	v_mov_b64_e32 v[80:81], 0
	v_mov_b64_e32 v[82:83], 0
	v_mov_b64_e32 v[84:85], 0
	v_mov_b64_e32 v[86:87], 0
	v_mov_b64_e32 v[88:89], 0
	v_mov_b64_e32 v[90:91], 0
	v_mov_b64_e32 v[92:93], 0
	v_mov_b64_e32 v[94:95], 0
	v_mov_b64_e32 v[96:97], 0
	v_mov_b64_e32 v[98:99], 0
	v_mov_b64_e32 v[100:101], 0
	v_mov_b64_e32 v[102:103], 0
	v_mov_b64_e32 v[104:105], 0
	v_mov_b64_e32 v[106:107], 0
	v_mov_b64_e32 v[108:109], 0
	v_mov_b64_e32 v[110:111], 0
	v_mov_b64_e32 v[112:113], 0
	v_mov_b64_e32 v[114:115], 0
	v_mov_b64_e32 v[116:117], 0
	v_mov_b64_e32 v[118:119], 0
	v_mov_b64_e32 v[120:121], 0
	v_mov_b64_e32 v[122:123], 0
	v_mov_b64_e32 v[124:125], 0
	v_mov_b64_e32 v[126:127], 0
	s_nop 1
	v_add_u32_e32 v230, 0x10000, v143
.LBB0_299:
	ds_read_b128 v[128:131], v230
	ds_read_b128 v[152:155], v230 offset:1024
	ds_read_b128 v[158:161], v230 offset:2048
	ds_read_b128 v[162:165], v230 offset:3072
	s_add_u32 s28, s0, 0xfffc0080
	s_addc_u32 s29, s1, -1
	s_cmp_eq_u32 s27, 12
	s_cselect_b32 s31, s20, s29
	s_cselect_b32 s30, s34, s28
	s_cselect_b32 s29, s35, s26
	s_cselect_b32 s28, s36, s37
	v_lshl_add_u64 v[182:183], s[0:1], 0, v[148:149]
	s_add_i32 m0, s58, 0xc000
	ds_read_b128 v[166:169], v141
	ds_read_b128 v[170:173], v141 offset:1024
	ds_read_b128 v[174:177], v141 offset:2048
	ds_read_b128 v[178:181], v141 offset:3072
	ds_read_b128 v[186:189], v141 offset:4096
	ds_read_b128 v[194:197], v141 offset:5120
	ds_read_b128 v[198:201], v141 offset:6144
	ds_read_b128 v[202:205], v141 offset:7168
	global_load_lds_dwordx4 v[182:183], off
	v_lshl_add_u64 v[182:183], s[0:1], 0, v[150:151]
	s_add_i32 m0, s58, 0xe000
	s_nop 0
	global_load_lds_dwordx4 v[182:183], off
	ds_read_b128 v[206:209], v230 offset:16384
	ds_read_b128 v[210:213], v230 offset:17408
	ds_read_b128 v[214:217], v230 offset:18432
	ds_read_b128 v[242:245], v230 offset:19456
	s_waitcnt vmcnt(8) lgkmcnt(0)
	s_barrier
	v_mfma_f32_16x16x32_bf16 v[124:127], v[128:131], v[166:169], v[124:127]
	v_mfma_f32_16x16x32_bf16 v[120:123], v[158:161], v[166:169], v[120:123]
	v_mfma_f32_16x16x32_bf16 v[116:119], v[128:131], v[174:177], v[116:119]
	v_mfma_f32_16x16x32_bf16 v[112:115], v[158:161], v[174:177], v[112:115]
	v_mfma_f32_16x16x32_bf16 v[108:111], v[128:131], v[186:189], v[108:111]
	v_mfma_f32_16x16x32_bf16 v[104:107], v[158:161], v[186:189], v[104:107]
	v_mfma_f32_16x16x32_bf16 v[100:103], v[128:131], v[198:201], v[100:103]
	v_mfma_f32_16x16x32_bf16 v[96:99], v[158:161], v[198:201], v[96:99]
	v_mfma_f32_16x16x32_bf16 v[124:127], v[152:155], v[170:173], v[124:127]
	v_mfma_f32_16x16x32_bf16 v[120:123], v[162:165], v[170:173], v[120:123]
	v_mfma_f32_16x16x32_bf16 v[116:119], v[152:155], v[178:181], v[116:119]
	v_mfma_f32_16x16x32_bf16 v[112:115], v[162:165], v[178:181], v[112:115]
	v_mfma_f32_16x16x32_bf16 v[108:111], v[152:155], v[194:197], v[108:111]
	v_mfma_f32_16x16x32_bf16 v[104:107], v[162:165], v[194:197], v[104:107]
	v_mfma_f32_16x16x32_bf16 v[100:103], v[152:155], v[202:205], v[100:103]
	v_mfma_f32_16x16x32_bf16 v[96:99], v[162:165], v[202:205], v[96:99]
	v_mfma_f32_16x16x32_bf16 v[92:95], v[206:209], v[166:169], v[92:95]
	v_mfma_f32_16x16x32_bf16 v[88:91], v[214:217], v[166:169], v[88:91]
	v_mfma_f32_16x16x32_bf16 v[84:87], v[206:209], v[174:177], v[84:87]
	v_mfma_f32_16x16x32_bf16 v[80:83], v[214:217], v[174:177], v[80:83]
	v_mfma_f32_16x16x32_bf16 v[76:79], v[206:209], v[186:189], v[76:79]
	v_mfma_f32_16x16x32_bf16 v[72:75], v[214:217], v[186:189], v[72:75]
	v_mfma_f32_16x16x32_bf16 v[68:71], v[206:209], v[198:201], v[68:71]
	v_mfma_f32_16x16x32_bf16 v[64:67], v[214:217], v[198:201], v[64:67]
	v_mfma_f32_16x16x32_bf16 v[92:95], v[210:213], v[170:173], v[92:95]
	v_mfma_f32_16x16x32_bf16 v[88:91], v[242:245], v[170:173], v[88:91]
	v_mfma_f32_16x16x32_bf16 v[84:87], v[210:213], v[178:181], v[84:87]
	v_mfma_f32_16x16x32_bf16 v[80:83], v[242:245], v[178:181], v[80:83]
	v_mfma_f32_16x16x32_bf16 v[76:79], v[210:213], v[194:197], v[76:79]
	v_mfma_f32_16x16x32_bf16 v[72:75], v[242:245], v[194:197], v[72:75]
	v_mfma_f32_16x16x32_bf16 v[68:71], v[210:213], v[202:205], v[68:71]
	v_mfma_f32_16x16x32_bf16 v[64:67], v[242:245], v[202:205], v[64:67]
	s_barrier
	s_mov_b32 m0, s39
	v_lshl_add_u64 v[182:183], s[28:29], 0, v[134:135]
	global_load_lds_dwordx4 v[182:183], off
	v_lshl_add_u64 v[190:191], s[28:29], 0, v[138:139]
	s_mov_b32 m0, s59
	s_nop 0
	global_load_lds_dwordx4 v[190:191], off
	s_mov_b32 m0, s58
	v_lshl_add_u64 v[246:247], s[30:31], 0, v[132:133]
	ds_read_b128 v[166:169], v141 offset:16384
	ds_read_b128 v[170:173], v141 offset:17408
	ds_read_b128 v[174:177], v141 offset:18432
	ds_read_b128 v[178:181], v141 offset:19456
	ds_read_b128 v[186:189], v141 offset:20480
	ds_read_b128 v[194:197], v141 offset:21504
	ds_read_b128 v[198:201], v141 offset:22528
	ds_read_b128 v[202:205], v141 offset:23552
	global_load_lds_dwordx4 v[246:247], off
	v_lshl_add_u64 v[248:249], s[30:31], 0, v[136:137]
	s_mov_b32 m0, s60
	s_nop 0
	global_load_lds_dwordx4 v[248:249], off
	s_waitcnt vmcnt(6) lgkmcnt(0)
	s_barrier
	s_cmp_lg_u32 s100, 0
	s_cbranch_scc1 .Lmskip_299_1
	v_mfma_f32_16x16x32_bf16 v[60:63], v[128:131], v[166:169], v[60:63]
	v_mfma_f32_16x16x32_bf16 v[56:59], v[158:161], v[166:169], v[56:59]
	v_mfma_f32_16x16x32_bf16 v[52:55], v[128:131], v[174:177], v[52:55]
	v_mfma_f32_16x16x32_bf16 v[48:51], v[158:161], v[174:177], v[48:51]
	v_mfma_f32_16x16x32_bf16 v[44:47], v[128:131], v[186:189], v[44:47]
	v_mfma_f32_16x16x32_bf16 v[40:43], v[158:161], v[186:189], v[40:43]
	v_mfma_f32_16x16x32_bf16 v[36:39], v[128:131], v[198:201], v[36:39]
	v_mfma_f32_16x16x32_bf16 v[32:35], v[158:161], v[198:201], v[32:35]
	v_mfma_f32_16x16x32_bf16 v[60:63], v[152:155], v[170:173], v[60:63]
	v_mfma_f32_16x16x32_bf16 v[56:59], v[162:165], v[170:173], v[56:59]
	v_mfma_f32_16x16x32_bf16 v[52:55], v[152:155], v[178:181], v[52:55]
	v_mfma_f32_16x16x32_bf16 v[48:51], v[162:165], v[178:181], v[48:51]
	v_mfma_f32_16x16x32_bf16 v[44:47], v[152:155], v[194:197], v[44:47]
	v_mfma_f32_16x16x32_bf16 v[40:43], v[162:165], v[194:197], v[40:43]
	v_mfma_f32_16x16x32_bf16 v[36:39], v[152:155], v[202:205], v[36:39]
	v_mfma_f32_16x16x32_bf16 v[32:35], v[162:165], v[202:205], v[32:35]
	v_mfma_f32_16x16x32_bf16 v[28:31], v[206:209], v[166:169], v[28:31]
	v_mfma_f32_16x16x32_bf16 v[24:27], v[214:217], v[166:169], v[24:27]
	v_mfma_f32_16x16x32_bf16 v[20:23], v[206:209], v[174:177], v[20:23]
	v_mfma_f32_16x16x32_bf16 v[16:19], v[214:217], v[174:177], v[16:19]
	v_mfma_f32_16x16x32_bf16 v[12:15], v[206:209], v[186:189], v[12:15]
	v_mfma_f32_16x16x32_bf16 v[8:11], v[214:217], v[186:189], v[8:11]
	v_mfma_f32_16x16x32_bf16 v[4:7], v[206:209], v[198:201], v[4:7]
	v_mfma_f32_16x16x32_bf16 v[0:3], v[214:217], v[198:201], v[0:3]
	v_mfma_f32_16x16x32_bf16 v[28:31], v[210:213], v[170:173], v[28:31]
	v_mfma_f32_16x16x32_bf16 v[24:27], v[242:245], v[170:173], v[24:27]
	v_mfma_f32_16x16x32_bf16 v[20:23], v[210:213], v[178:181], v[20:23]
	v_mfma_f32_16x16x32_bf16 v[16:19], v[242:245], v[178:181], v[16:19]
	v_mfma_f32_16x16x32_bf16 v[12:15], v[210:213], v[194:197], v[12:15]
	v_mfma_f32_16x16x32_bf16 v[8:11], v[242:245], v[194:197], v[8:11]
	v_mfma_f32_16x16x32_bf16 v[4:7], v[210:213], v[202:205], v[4:7]
	v_mfma_f32_16x16x32_bf16 v[0:3], v[242:245], v[202:205], v[0:3]
.Lmskip_299_1:
	s_barrier
	s_add_u32 s46, s28, 0x40000
	s_addc_u32 s47, s29, 0
	s_mov_b32 m0, s61
	v_lshl_add_u64 v[128:129], s[46:47], 0, v[134:135]
	global_load_lds_dwordx4 v[128:129], off
	v_lshl_add_u64 v[128:129], s[46:47], 0, v[138:139]
	s_mov_b32 m0, s62
	s_nop 0
	global_load_lds_dwordx4 v[128:129], off
	ds_read_b128 v[128:131], v230 offset:32768
	ds_read_b128 v[152:155], v230 offset:33792
	ds_read_b128 v[158:161], v230 offset:34816
	ds_read_b128 v[162:165], v230 offset:35840
	s_add_u32 s30, s30, 0x40000
	s_addc_u32 s31, s31, 0
	s_mov_b32 m0, s63
	v_lshl_add_u64 v[206:207], s[30:31], 0, v[132:133]
	ds_read_b128 v[166:169], v141 offset:32768
	ds_read_b128 v[170:173], v141 offset:33792
	ds_read_b128 v[174:177], v141 offset:34816
	ds_read_b128 v[178:181], v141 offset:35840
	ds_read_b128 v[186:189], v141 offset:36864
	ds_read_b128 v[194:197], v141 offset:37888
	ds_read_b128 v[198:201], v141 offset:38912
	ds_read_b128 v[202:205], v141 offset:39936
	global_load_lds_dwordx4 v[206:207], off
	v_lshl_add_u64 v[206:207], s[30:31], 0, v[136:137]
	s_mov_b32 m0, s64
	s_nop 0
	global_load_lds_dwordx4 v[206:207], off
	ds_read_b128 v[206:209], v230 offset:49152
	ds_read_b128 v[210:213], v230 offset:50176
	ds_read_b128 v[214:217], v230 offset:51200
	ds_read_b128 v[242:245], v230 offset:52224
	s_waitcnt vmcnt(8) lgkmcnt(0)
	s_barrier
	v_mfma_f32_16x16x32_bf16 v[124:127], v[128:131], v[166:169], v[124:127]
	v_mfma_f32_16x16x32_bf16 v[120:123], v[158:161], v[166:169], v[120:123]
	v_mfma_f32_16x16x32_bf16 v[116:119], v[128:131], v[174:177], v[116:119]
	v_mfma_f32_16x16x32_bf16 v[112:115], v[158:161], v[174:177], v[112:115]
	v_mfma_f32_16x16x32_bf16 v[108:111], v[128:131], v[186:189], v[108:111]
	v_mfma_f32_16x16x32_bf16 v[104:107], v[158:161], v[186:189], v[104:107]
	v_mfma_f32_16x16x32_bf16 v[100:103], v[128:131], v[198:201], v[100:103]
	v_mfma_f32_16x16x32_bf16 v[96:99], v[158:161], v[198:201], v[96:99]
	v_mfma_f32_16x16x32_bf16 v[124:127], v[152:155], v[170:173], v[124:127]
	v_mfma_f32_16x16x32_bf16 v[120:123], v[162:165], v[170:173], v[120:123]
	v_mfma_f32_16x16x32_bf16 v[116:119], v[152:155], v[178:181], v[116:119]
	v_mfma_f32_16x16x32_bf16 v[112:115], v[162:165], v[178:181], v[112:115]
	v_mfma_f32_16x16x32_bf16 v[108:111], v[152:155], v[194:197], v[108:111]
	v_mfma_f32_16x16x32_bf16 v[104:107], v[162:165], v[194:197], v[104:107]
	v_mfma_f32_16x16x32_bf16 v[100:103], v[152:155], v[202:205], v[100:103]
	v_mfma_f32_16x16x32_bf16 v[96:99], v[162:165], v[202:205], v[96:99]
	v_mfma_f32_16x16x32_bf16 v[92:95], v[206:209], v[166:169], v[92:95]
	v_mfma_f32_16x16x32_bf16 v[88:91], v[214:217], v[166:169], v[88:91]
	v_mfma_f32_16x16x32_bf16 v[84:87], v[206:209], v[174:177], v[84:87]
	v_mfma_f32_16x16x32_bf16 v[80:83], v[214:217], v[174:177], v[80:83]
	v_mfma_f32_16x16x32_bf16 v[76:79], v[206:209], v[186:189], v[76:79]
	v_mfma_f32_16x16x32_bf16 v[72:75], v[214:217], v[186:189], v[72:75]
	v_mfma_f32_16x16x32_bf16 v[68:71], v[206:209], v[198:201], v[68:71]
	v_mfma_f32_16x16x32_bf16 v[64:67], v[214:217], v[198:201], v[64:67]
	v_mfma_f32_16x16x32_bf16 v[92:95], v[210:213], v[170:173], v[92:95]
	v_mfma_f32_16x16x32_bf16 v[88:91], v[242:245], v[170:173], v[88:91]
	v_mfma_f32_16x16x32_bf16 v[84:87], v[210:213], v[178:181], v[84:87]
	v_mfma_f32_16x16x32_bf16 v[80:83], v[242:245], v[178:181], v[80:83]
	v_mfma_f32_16x16x32_bf16 v[76:79], v[210:213], v[194:197], v[76:79]
	v_mfma_f32_16x16x32_bf16 v[72:75], v[242:245], v[194:197], v[72:75]
	v_mfma_f32_16x16x32_bf16 v[68:71], v[210:213], v[202:205], v[68:71]
	v_mfma_f32_16x16x32_bf16 v[64:67], v[242:245], v[202:205], v[64:67]
	s_barrier
	s_mov_b32 m0, s68
	v_lshl_add_u64 v[182:183], v[182:183], 0, s[24:25]
	global_load_lds_dwordx4 v[182:183], off
	v_lshl_add_u64 v[182:183], v[190:191], 0, s[24:25]
	s_mov_b32 m0, s69
	s_nop 0
	global_load_lds_dwordx4 v[182:183], off
	s_mov_b32 m0, s70
	v_lshl_add_u64 v[182:183], v[246:247], 0, s[24:25]
	ds_read_b128 v[166:169], v141 offset:49152
	ds_read_b128 v[170:173], v141 offset:50176
	ds_read_b128 v[174:177], v141 offset:51200
	ds_read_b128 v[178:181], v141 offset:52224
	ds_read_b128 v[186:189], v141 offset:53248
	ds_read_b128 v[194:197], v141 offset:54272
	ds_read_b128 v[198:201], v141 offset:55296
	ds_read_b128 v[202:205], v141 offset:56320
	global_load_lds_dwordx4 v[182:183], off
	v_lshl_add_u64 v[182:183], v[248:249], 0, s[24:25]
	s_mov_b32 m0, s71
	s_nop 0
	global_load_lds_dwordx4 v[182:183], off
	s_waitcnt vmcnt(6) lgkmcnt(0)
	s_barrier
	s_cmp_lg_u32 s100, 0
	s_cbranch_scc1 .Lmskip_299_3
	v_mfma_f32_16x16x32_bf16 v[60:63], v[128:131], v[166:169], v[60:63]
	v_mfma_f32_16x16x32_bf16 v[56:59], v[158:161], v[166:169], v[56:59]
	v_mfma_f32_16x16x32_bf16 v[52:55], v[128:131], v[174:177], v[52:55]
	v_mfma_f32_16x16x32_bf16 v[48:51], v[158:161], v[174:177], v[48:51]
	v_mfma_f32_16x16x32_bf16 v[44:47], v[128:131], v[186:189], v[44:47]
	v_mfma_f32_16x16x32_bf16 v[40:43], v[158:161], v[186:189], v[40:43]
	v_mfma_f32_16x16x32_bf16 v[36:39], v[128:131], v[198:201], v[36:39]
	v_mfma_f32_16x16x32_bf16 v[32:35], v[158:161], v[198:201], v[32:35]
	v_mfma_f32_16x16x32_bf16 v[60:63], v[152:155], v[170:173], v[60:63]
	v_mfma_f32_16x16x32_bf16 v[56:59], v[162:165], v[170:173], v[56:59]
	v_mfma_f32_16x16x32_bf16 v[52:55], v[152:155], v[178:181], v[52:55]
	v_mfma_f32_16x16x32_bf16 v[48:51], v[162:165], v[178:181], v[48:51]
	v_mfma_f32_16x16x32_bf16 v[44:47], v[152:155], v[194:197], v[44:47]
	v_mfma_f32_16x16x32_bf16 v[40:43], v[162:165], v[194:197], v[40:43]
	v_mfma_f32_16x16x32_bf16 v[36:39], v[152:155], v[202:205], v[36:39]
	v_mfma_f32_16x16x32_bf16 v[32:35], v[162:165], v[202:205], v[32:35]
	v_mfma_f32_16x16x32_bf16 v[28:31], v[206:209], v[166:169], v[28:31]
	v_mfma_f32_16x16x32_bf16 v[24:27], v[214:217], v[166:169], v[24:27]
	v_mfma_f32_16x16x32_bf16 v[20:23], v[206:209], v[174:177], v[20:23]
	v_mfma_f32_16x16x32_bf16 v[16:19], v[214:217], v[174:177], v[16:19]
	v_mfma_f32_16x16x32_bf16 v[12:15], v[206:209], v[186:189], v[12:15]
	v_mfma_f32_16x16x32_bf16 v[8:11], v[214:217], v[186:189], v[8:11]
	v_mfma_f32_16x16x32_bf16 v[4:7], v[206:209], v[198:201], v[4:7]
	v_mfma_f32_16x16x32_bf16 v[0:3], v[214:217], v[198:201], v[0:3]
	v_mfma_f32_16x16x32_bf16 v[28:31], v[210:213], v[170:173], v[28:31]
	v_mfma_f32_16x16x32_bf16 v[24:27], v[242:245], v[170:173], v[24:27]
	v_mfma_f32_16x16x32_bf16 v[20:23], v[210:213], v[178:181], v[20:23]
	v_mfma_f32_16x16x32_bf16 v[16:19], v[242:245], v[178:181], v[16:19]
	v_mfma_f32_16x16x32_bf16 v[12:15], v[210:213], v[194:197], v[12:15]
	v_mfma_f32_16x16x32_bf16 v[8:11], v[242:245], v[194:197], v[8:11]
	v_mfma_f32_16x16x32_bf16 v[4:7], v[210:213], v[202:205], v[4:7]
	v_mfma_f32_16x16x32_bf16 v[0:3], v[242:245], v[202:205], v[0:3]
.Lmskip_299_3:
	s_barrier
	s_add_u32 s28, s28, 0x40080
	s_addc_u32 s29, s29, 0
	s_mov_b32 m0, s52
	v_lshl_add_u64 v[128:129], s[28:29], 0, v[134:135]
	global_load_lds_dwordx4 v[128:129], off
	v_lshl_add_u64 v[128:129], s[28:29], 0, v[138:139]
	s_mov_b32 m0, s50
	s_nop 0
	global_load_lds_dwordx4 v[128:129], off
	s_add_i32 s27, s27, 2
	s_add_u32 s0, s0, 0x100
	s_addc_u32 s1, s1, 0
	s_add_u32 s37, s37, 0x100
	s_addc_u32 s26, s26, 0
	s_cmp_gt_u32 s27, 13
	s_cbranch_scc0 .LBB0_299
	s_lshl_b32 s20, s53, 8
	s_add_i32 s20, s20, s66
	s_cmp_eq_u32 s100, 2
	s_cselect_b32 vcc_hi, 0x80, 0
	s_cselect_b32 vcc_lo, 8, 0
	s_add_i32 s20, s20, vcc_hi
	s_add_i32 s67, s67, vcc_lo
	s_add_i32 s84, s84, vcc_lo
	s_add_i32 s85, s85, vcc_lo
	s_add_i32 s92, s92, vcc_lo
	s_lshl_b32 s46, s38, 8
	s_cmp_lg_u32 s33, 0
	v_or_b32_e32 v154, s20, v140
	v_or_b32_e32 v152, s46, v144
	s_cselect_b64 s[28:29], -1, 0
	s_movk_i32 s33, 0x3fff
	s_and_b64 vcc, exec, s[28:29]
	v_and_b32_e32 v157, 0xcf, v154
	v_cmp_lt_i32_e64 s[0:1], s33, v152
	s_cbranch_vccz .LBB0_306
	s_ashr_i32 s30, s20, 8
	v_cvt_pk_bf16_f32 v128, v124, v125
	v_cvt_pk_bf16_f32 v129, v126, v127
	v_cvt_pk_bf16_f32 v130, v120, v121
	v_cvt_pk_bf16_f32 v131, v122, v123
	s_and_saveexec_b64 s[26:27], s[0:1]
	s_xor_b64 s[0:1], exec, s[26:27]
	s_cbranch_execz .LBB0_303
	s_add_i32 s26, s46, 0xffffc000
	s_lshr_b32 s26, s26, 7
	v_lshl_add_u32 v184, v157, 4, s26
	s_ashr_i32 s31, s30, 31
	v_lshl_add_u64 v[158:159], v[184:185], 0, s[30:31]
	v_lshlrev_b64 v[158:159], 9, v[158:159]
	v_lshl_add_u64 v[158:159], v[146:147], 0, v[158:159]
	global_store_dwordx4 v[158:159], v[128:131], off

.LBB0_388:
	s_cmp_lg_u32 s100, 0
	s_cbranch_scc1 .Lg1h_nost
	s_addk_i32 s20, 0x80
	s_nop 0
	v_or_b32_e32 v68, s20, v140
	s_and_b64 vcc, exec, s[36:37]
	v_and_b32_e32 v70, 0xcf, v68
	s_cbranch_vccnz .LBB0_394
	s_ashr_i32 s0, s20, 8
	v_cmp_lt_i32_e32 vcc, s33, v152
	v_cvt_pk_bf16_f32 v64, v60, v61
	v_cvt_pk_bf16_f32 v65, v62, v63
	v_cvt_pk_bf16_f32 v66, v56, v57
	v_cvt_pk_bf16_f32 v67, v58, v59
	s_and_saveexec_b64 s[26:27], vcc
	s_xor_b64 s[28:29], exec, s[26:27]
	s_cbranch_execz .LBB0_391
	s_add_i32 s1, s46, 0xffffc000
	s_lshr_b32 s1, s1, 7
	v_lshl_add_u32 v184, v70, 4, s1
	s_ashr_i32 s1, s0, 31
	v_lshl_add_u64 v[72:73], v[184:185], 0, s[0:1]
	v_lshlrev_b64 v[72:73], 9, v[72:73]
	v_lshl_add_u64 v[72:73], v[146:147], 0, v[72:73]
	global_store_dwordx4 v[72:73], v[64:67], off
